# lagging wave group: next-tile staging addresses from 4 SGPR bases computed once per unit (2 VALU per tile instead of 7)
# speedup vs baseline: 1.0168x; 1.0035x over previous
; #define SLOAD(t) do { const long r0_ = TROW(t); const bf16_t* vp_ = Vh + r0_ * LDV + vgo0; const bf16_t* kp_ = Kh + r0_ * LDKK + kgo0; \
;     vs0 = *reinterpret_cast<const bf16x8*>(vp_); vs1 = *reinterpret_cast<const bf16x8*>(vp_ + 64); \
;     ks0 = *reinterpret_cast<const bf16x8*>(kp_); ks1 = *reinterpret_cast<const bf16x8*>(kp_ + 64); ks2 = *reinterpret_cast<const bf16x8*>(kp_ + 128); } while (0)
; #define SWRITE(b) do { *(bf16x8*)(V_lds + (b) * SHM_V + vst0) = vs0; *(bf16x8*)(V_lds + (b) * SHM_V + vst0 + 1024) = vs1; \
;     *(bf16x8*)(K_lds + (b) * SHM_K + klo0) = ks0; *(bf16x8*)(K_lds + (b) * SHM_K + klo0 + 128) = ks1; *(bf16x8*)(K_lds + (b) * SHM_K + klo0 + 256) = ks2; } while (0)
; #define SWAIT() asm volatile("s_waitcnt vmcnt(0)" ::: "memory")
; #define QSTEP(d, A, B, NA, NB) do { if ((d) + 2 < 12) { NA = KLD((d) + 2, 0); NB = KLD((d) + 2, 1); } SBAR(); \
;     p0 = __builtin_amdgcn_mfma_f32_32x32x16_bf16(A, qr[d], p0, 0, 0, 0); p1 = __builtin_amdgcn_mfma_f32_32x32x16_bf16(B, qr[d], p1, 0, 0, 0); SBAR(); } while (0)
; #define SWAIT() asm volatile("s_waitcnt vmcnt(0)" ::: "memory")
; #define BARRIER() asm volatile("s_waitcnt lgkmcnt(0)\n\ts_barrier" ::: "memory")
; __device__ __forceinline__ void qkt2(f32x16& p0, f32x16& p1, const char* Ks, const bf16x8* qr, const int* kb4) {
;     ...
;   p0 = f32x16{}; p1 = f32x16{};
;   bf16x8 a0 = KLD(0, 0), b0 = KLD(0, 1), a1 = KLD(1, 0), b1 = KLD(1, 1), a2, b2;
;     ...
;   QSTEP(0, a0, b0, a2, b2); QSTEP(1, a1, b1, a0, b0); QSTEP(2, a2, b2, a1, b1);
;   QSTEP(3, a0, b0, a2, b2); QSTEP(4, a1, b1, a0, b0); QSTEP(5, a2, b2, a1, b1);
;   QSTEP(6, a0, b0, a2, b2); QSTEP(7, a1, b1, a0, b0); QSTEP(8, a2, b2, a1, b1);
;   QSTEP(9, a0, b0, a2, b2); QSTEP(10, a1, b1, a0, b0); QSTEP(11, a2, b2, a1, b1);
;     ...
; }
; __device__ __forceinline__ void attn_unit2(const bf16_t* __restrict__ Qb, const bf16_t* __restrict__ Kh, const bf16_t* __restrict__ Vh, ...
;     ...
;   f32x16 p0, p1; float mn, al = 1.f; bf16x8 pa0, pa1, pa2, pa3; constexpr int NT = NCHUNK;
;   SLOAD(0); SWAIT(); SWRITE(0); BARRIER();
;     ...
;   if (wid < 4) {
;     ...
;     SLOAD(1);
;     for (int t = 0; t + 1 < NT; t += 2) { A_TILE(t, 0); A_TILE(t + 1, 1); }
;     A_TILE(NT - 1, 0);
;     BARRIER();
;     ...
;   } else {
;     SLOAD(1); BARRIER();
;     ...
;     for (int t = 0; t + 1 < NT; t += 2) { B_TILE(t, 0); B_TILE(t + 1, 1); }
.LBB0_440:
	s_cmp_lg_u32 0, -1
	s_cselect_b32 s0, 0, 0
	s_addk_i32 s0, 0x4000
	v_add_u32_e32 v215, s0, v213
	s_add_u32 s0, s40, s39
	s_addc_u32 s1, s41, 0
	v_lshl_add_u64 v[190:191], v[186:187], 1, s[0:1]
	s_lshl_b32 s0, s19, 3
	s_and_b32 s0, s0, 0xe00
	s_waitcnt lgkmcnt(0)
	s_barrier
	s_add_u32 s0, s22, s0
	v_mov_b32_e32 v14, v185
	v_mov_b32_e32 v15, v185
	s_addc_u32 s1, s23, 0
	v_mov_b32_e32 v0, v185
	v_mov_b32_e32 v1, v185
	v_mov_b32_e32 v2, v185
	v_mov_b32_e32 v3, v185
	v_mov_b32_e32 v4, v185
	v_mov_b32_e32 v5, v185
	v_mov_b32_e32 v6, v185
	v_mov_b32_e32 v7, v185
	v_mov_b32_e32 v8, v185
	v_mov_b32_e32 v9, v185
	v_mov_b32_e32 v10, v185
	v_mov_b32_e32 v11, v185
	v_mov_b32_e32 v12, v185
	v_mov_b32_e32 v13, v185
	v_mov_b64_e32 v[62:63], v[14:15]
	v_mov_b64_e32 v[46:47], v[14:15]
	v_mov_b64_e32 v[30:31], v[14:15]
	s_waitcnt vmcnt(4)
	v_mov_b64_e32 v[166:167], v[146:147]
	s_waitcnt vmcnt(3)
	v_mov_b64_e32 v[170:171], v[150:151]
	s_waitcnt vmcnt(2)
	v_mov_b64_e32 v[174:175], v[154:155]
	s_waitcnt vmcnt(1)
	v_mov_b64_e32 v[178:179], v[158:159]
	s_waitcnt vmcnt(0)
	v_mov_b64_e32 v[182:183], v[162:163]
	s_mov_b32 s42, 0
	v_add_u32_e32 v216, 0xe000, v210
	v_add_u32_e32 v217, 0xe000, v209
	v_add_u32_e32 v218, 0xe000, v208
	v_add_u32_e32 v219, 0xe000, v207
	v_lshl_add_u64 v[192:193], v[188:189], 1, s[0:1]
	v_mov_b32_e32 v220, 0xf149f2ca
	v_mov_b32_e32 v214, 0
	v_mov_b64_e32 v[60:61], v[12:13]
	v_mov_b64_e32 v[58:59], v[10:11]
	v_mov_b64_e32 v[56:57], v[8:9]
	v_mov_b64_e32 v[54:55], v[6:7]
	v_mov_b64_e32 v[52:53], v[4:5]
	v_mov_b64_e32 v[50:51], v[2:3]
	v_mov_b64_e32 v[48:49], v[0:1]
	v_mov_b64_e32 v[44:45], v[12:13]
	v_mov_b64_e32 v[42:43], v[10:11]
	v_mov_b64_e32 v[40:41], v[8:9]
	v_mov_b64_e32 v[38:39], v[6:7]
	v_mov_b64_e32 v[36:37], v[4:5]
	v_mov_b64_e32 v[34:35], v[2:3]
	v_mov_b64_e32 v[32:33], v[0:1]
	v_mov_b64_e32 v[28:29], v[12:13]
	v_mov_b64_e32 v[26:27], v[10:11]
	v_mov_b64_e32 v[24:25], v[8:9]
	v_mov_b64_e32 v[22:23], v[6:7]
	v_mov_b64_e32 v[20:21], v[4:5]
	v_mov_b64_e32 v[18:19], v[2:3]
	v_mov_b64_e32 v[16:17], v[0:1]
	s_mov_b32 s44, 0
	v_mov_b64_e32 v[164:165], v[144:145]
	v_mov_b64_e32 v[168:169], v[148:149]
	v_mov_b64_e32 v[172:173], v[152:153]
	v_mov_b64_e32 v[176:177], v[156:157]
	v_mov_b64_e32 v[180:181], v[160:161]
	v_readlane_b32 s0, v247, 14
	v_readlane_b32 s1, v247, 15
	s_load_dwordx4 s[52:55], s[0:1], 0xc0
	s_waitcnt lgkmcnt(0)
	s_add_u32 s56, s52, s28
	s_addc_u32 s57, s53, 0
	s_add_u32 s58, s52, s29
	s_addc_u32 s59, s53, 0
	s_add_u32 s60, s52, 0x28780000
	s_addc_u32 s61, s53, 0
	s_add_u32 s62, s52, 0x1b360000
	s_addc_u32 s63, s53, 0
.LBB0_441:
	ds_read_b128 v[64:67], v210 offset:32768
	ds_read_b128 v[80:83], v210 offset:45056
	ds_read_b128 v[222:225], v209 offset:32768
	ds_read_b128 v[226:229], v209 offset:45056
	ds_read_b128 v[230:233], v208 offset:32768
	ds_read_b128 v[234:237], v208 offset:45056
	s_waitcnt vmcnt(0)
	v_lshl_add_u64 v[144:145], s[56:57], 0, v[192:193]
	v_lshl_add_u64 v[146:147], s[58:59], 0, v[190:191]
	s_waitcnt lgkmcnt(4)
	v_mfma_f32_32x32x16_bf16 v[64:79], v[64:67], v[96:99], 0
	v_mfma_f32_32x32x16_bf16 v[80:95], v[80:83], v[96:99], 0
	ds_write_b128 v212, v[164:167] offset:16384
	ds_write_b128 v212, v[168:171] offset:17408
	ds_read_b128 v[238:241], v207 offset:32768
	ds_read_b128 v[242:245], v207 offset:45056
	s_waitcnt lgkmcnt(6)
	v_mfma_f32_32x32x16_bf16 v[64:79], v[222:225], v[100:103], v[64:79]
	v_mfma_f32_32x32x16_bf16 v[80:95], v[226:229], v[100:103], v[80:95]
	ds_write_b128 v211, v[172:175] offset:57344
	ds_write_b128 v211, v[176:179] offset:57472
	ds_read_b128 v[222:225], v210 offset:32896
	ds_read_b128 v[226:229], v210 offset:45184
	global_load_dwordx4 v[164:167], v[144:145], off offset:256
	global_load_dwordx4 v[168:171], v[144:145], off offset:384
	s_waitcnt lgkmcnt(8)
	v_mfma_f32_32x32x16_bf16 v[64:79], v[230:233], v[104:107], v[64:79]
	v_mfma_f32_32x32x16_bf16 v[80:95], v[234:237], v[104:107], v[80:95]
	ds_write_b128 v211, v[180:183] offset:57600
	ds_read_b128 v[230:233], v209 offset:32896
	ds_read_b128 v[234:237], v209 offset:45184
	global_load_dwordx4 v[172:175], v[146:147], off
	global_load_dwordx4 v[176:179], v[146:147], off offset:128
	s_waitcnt lgkmcnt(7)
	v_mfma_f32_32x32x16_bf16 v[64:79], v[238:241], v[108:111], v[64:79]
	v_mfma_f32_32x32x16_bf16 v[80:95], v[242:245], v[108:111], v[80:95]
	ds_read_b128 v[238:241], v208 offset:32896
	ds_read_b128 v[242:245], v208 offset:45184
	global_load_dwordx4 v[180:183], v[146:147], off offset:256
	s_waitcnt lgkmcnt(5)
	v_mfma_f32_32x32x16_bf16 v[64:79], v[222:225], v[112:115], v[64:79]
	v_mfma_f32_32x32x16_bf16 v[80:95], v[226:229], v[112:115], v[80:95]
	ds_read_b128 v[222:225], v207 offset:32896
	ds_read_b128 v[226:229], v207 offset:45184
	s_waitcnt lgkmcnt(4)
	v_mfma_f32_32x32x16_bf16 v[64:79], v[230:233], v[116:119], v[64:79]
	v_mfma_f32_32x32x16_bf16 v[80:95], v[234:237], v[116:119], v[80:95]
	ds_read_b128 v[230:233], v210 offset:33024
	ds_read_b128 v[234:237], v210 offset:45312
	s_waitcnt lgkmcnt(4)
	v_mfma_f32_32x32x16_bf16 v[64:79], v[238:241], v[120:123], v[64:79]
	v_mfma_f32_32x32x16_bf16 v[80:95], v[242:245], v[120:123], v[80:95]
	ds_read_b128 v[238:241], v209 offset:33024
	ds_read_b128 v[242:245], v209 offset:45312
	s_waitcnt lgkmcnt(4)
	v_mfma_f32_32x32x16_bf16 v[64:79], v[222:225], v[124:127], v[64:79]
	v_mfma_f32_32x32x16_bf16 v[80:95], v[226:229], v[124:127], v[80:95]
	ds_read_b128 v[222:225], v208 offset:33024
	ds_read_b128 v[226:229], v208 offset:45312
	s_waitcnt lgkmcnt(4)
	v_mfma_f32_32x32x16_bf16 v[64:79], v[230:233], v[132:135], v[64:79]
	v_mfma_f32_32x32x16_bf16 v[80:95], v[234:237], v[132:135], v[80:95]
	ds_read_b128 v[230:233], v207 offset:33024
	ds_read_b128 v[234:237], v207 offset:45312
	s_waitcnt lgkmcnt(4)
	v_mfma_f32_32x32x16_bf16 v[64:79], v[238:241], v[140:143], v[64:79]
	v_mfma_f32_32x32x16_bf16 v[80:95], v[242:245], v[140:143], v[80:95]
	s_waitcnt lgkmcnt(2)
	v_mfma_f32_32x32x16_bf16 v[64:79], v[222:225], v[128:131], v[64:79]
	v_mfma_f32_32x32x16_bf16 v[80:95], v[226:229], v[128:131], v[80:95]
	s_waitcnt lgkmcnt(0)
	v_mfma_f32_32x32x16_bf16 v[64:79], v[230:233], v[136:139], v[64:79]
	v_mfma_f32_32x32x16_bf16 v[80:95], v[234:237], v[136:139], v[80:95]
	s_cmp_eq_u32 s42, 0
	s_cbranch_scc1 .Lmask0_b
	s_nop 9

; #define SBAR() __builtin_amdgcn_sched_barrier(0)
; __device__ __forceinline__ void finishSM(f32x16& p0, f32x16& p1, float alpha, float& l_reg, bf16x8& pa0, bf16x8& pa1, bf16x8& pa2, bf16x8& pa3) {
; #pragma unroll
;   for (int r = 0; r < 16; ++r) p1[r] = __builtin_amdgcn_exp2f(p1[r]);
;   float ps = 0;
; #pragma unroll
;   for (int r = 0; r < 16; ++r) ps += p0[r];
; #pragma unroll
;   for (int r = 0; r < 16; ++r) ps += p1[r];
;   { auto rr = __builtin_amdgcn_permlane32_swap(__float_as_uint(ps), __float_as_uint(ps), false, false);
;     ps = __uint_as_float(rr[0]) + __uint_as_float(rr[1]); }
;   l_reg = l_reg * alpha + ps;
;     ...
;   PK4(p0, 0, pa0); PK4(p0, 8, pa1); PK4(p1, 0, pa2); PK4(p1, 8, pa3);
; __device__ __forceinline__ void pv2(f32x16* o, int vb, bf16x8 pa0, bf16x8 pa1, bf16x8 pa2, bf16x8 pa3) {
;   VSet X, Y;
;   SBAR(); v_issue<0>(X, vb); v_issue<1>(Y, vb);
;   asm volatile("s_waitcnt lgkmcnt(8)" ::: "memory"); SBAR(); v_mma(o[0], X, pa0, pa1, pa2, pa3); SBAR();
;   v_issue<2>(X, vb);
;   asm volatile("s_waitcnt lgkmcnt(8)" ::: "memory"); SBAR(); v_mma(o[1], Y, pa0, pa1, pa2, pa3); SBAR();
;   v_issue<3>(Y, vb);
;   asm volatile("s_waitcnt lgkmcnt(8)" ::: "memory"); SBAR(); v_mma(o[2], X, pa0, pa1, pa2, pa3); SBAR();
;   asm volatile("s_waitcnt lgkmcnt(0)" ::: "memory"); SBAR(); v_mma(o[3], Y, pa0, pa1, pa2, pa3); SBAR();
; }
.Lafter_b0:
	v_mul_f32_e32 v90, 0xbdd53b94, v220
	v_fmamk_f32 v64, v64, 0x3dd53b94, v90
	v_fmamk_f32 v65, v65, 0x3dd53b94, v90
	v_exp_f32_e32 v64, v64
	v_fmamk_f32 v66, v66, 0x3dd53b94, v90
	v_exp_f32_e32 v65, v65
	v_fmamk_f32 v67, v67, 0x3dd53b94, v90
	v_exp_f32_e32 v66, v66
	v_fmamk_f32 v68, v68, 0x3dd53b94, v90
	v_fmamk_f32 v73, v73, 0x3dd53b94, v90
	v_exp_f32_e32 v67, v67
	v_fmamk_f32 v69, v69, 0x3dd53b94, v90
	v_fmamk_f32 v92, v227, 0x3dd53b94, v90
	v_exp_f32_e32 v68, v68
	v_exp_f32_e32 v227, v73
	v_add_f32_e32 v73, 0, v64
	v_fmamk_f32 v70, v70, 0x3dd53b94, v90
	v_exp_f32_e32 v69, v69
	v_add_f32_e32 v73, v65, v73
	v_fmamk_f32 v71, v71, 0x3dd53b94, v90
	v_exp_f32_e32 v70, v70
	v_add_f32_e32 v73, v66, v73
	v_fmamk_f32 v91, v226, 0x3dd53b94, v90
	v_exp_f32_e32 v71, v71
	v_add_f32_e32 v73, v67, v73
	v_fmamk_f32 v93, v224, 0x3dd53b94, v90
	v_fmamk_f32 v94, v225, 0x3dd53b94, v90
	v_fmamk_f32 v95, v222, 0x3dd53b94, v90
	v_fmamk_f32 v222, v223, 0x3dd53b94, v90
	v_fmamk_f32 v78, v78, 0x3dd53b94, v90
	v_fmamk_f32 v79, v79, 0x3dd53b94, v90
	v_fmamk_f32 v80, v80, 0x3dd53b94, v90
	v_fmamk_f32 v81, v81, 0x3dd53b94, v90
	v_fmamk_f32 v82, v82, 0x3dd53b94, v90
	v_fmamk_f32 v83, v83, 0x3dd53b94, v90
	v_fmamk_f32 v84, v84, 0x3dd53b94, v90
	v_fmamk_f32 v85, v85, 0x3dd53b94, v90
	v_fmamk_f32 v86, v86, 0x3dd53b94, v90
	v_fmamk_f32 v87, v87, 0x3dd53b94, v90
	v_fmamk_f32 v88, v88, 0x3dd53b94, v90
	v_fmamk_f32 v89, v89, 0x3dd53b94, v90
	v_fmamk_f32 v76, v76, 0x3dd53b94, v90
	v_fmamk_f32 v77, v77, 0x3dd53b94, v90
	v_fmamk_f32 v74, v74, 0x3dd53b94, v90
	v_fmamk_f32 v75, v75, 0x3dd53b94, v90
	v_fmac_f32_e32 v90, 0x3dd53b94, v72
	v_exp_f32_e32 v72, v91
	v_add_f32_e32 v73, v68, v73
	v_exp_f32_e32 v91, v92
	v_add_f32_e32 v73, v69, v73
	v_exp_f32_e32 v92, v93
	v_add_f32_e32 v73, v70, v73
	v_exp_f32_e32 v93, v94
	v_add_f32_e32 v73, v71, v73
	v_exp_f32_e32 v94, v95
	v_add_f32_e32 v73, v72, v73
	v_exp_f32_e32 v95, v222
	v_add_f32_e32 v73, v91, v73
	v_exp_f32_e32 v78, v78
	v_add_f32_e32 v73, v92, v73
	v_exp_f32_e32 v79, v79
	v_add_f32_e32 v73, v93, v73
	v_exp_f32_e32 v80, v80
	v_add_f32_e32 v73, v94, v73
	v_exp_f32_e32 v81, v81
	v_add_f32_e32 v73, v95, v73
	v_exp_f32_e32 v82, v82
	v_add_f32_e32 v73, v78, v73
	v_exp_f32_e32 v83, v83
	v_add_f32_e32 v73, v79, v73
	v_exp_f32_e32 v84, v84
	v_add_f32_e32 v73, v80, v73
	v_exp_f32_e32 v85, v85
	v_add_f32_e32 v73, v81, v73
	v_exp_f32_e32 v86, v86
	v_add_f32_e32 v73, v82, v73
	v_exp_f32_e32 v87, v87
	v_add_f32_e32 v73, v83, v73
	v_exp_f32_e32 v88, v88
	v_add_f32_e32 v73, v84, v73
	v_exp_f32_e32 v89, v89
	v_add_f32_e32 v73, v85, v73
	v_exp_f32_e32 v224, v76
	v_add_f32_e32 v73, v86, v73
	v_exp_f32_e32 v77, v77
	v_add_f32_e32 v73, v87, v73
	v_exp_f32_e32 v225, v74
	v_add_f32_e32 v73, v88, v73
	v_exp_f32_e32 v226, v75
	v_add_f32_e32 v73, v89, v73
	v_add_f32_e32 v73, v224, v73
	v_exp_f32_e32 v90, v90
	v_add_f32_e32 v73, v77, v73
	v_add_f32_e32 v73, v225, v73
	v_add_f32_e32 v73, v226, v73
	v_add_f32_e32 v73, v227, v73
	v_add_f32_e32 v222, v90, v73
	v_mov_b32_e32 v223, v222
	s_nop 1
	v_permlane32_swap_b32_e32 v222, v223
	v_cvt_pk_bf16_f32 v64, v64, v65
	v_cvt_pk_bf16_f32 v65, v66, v67
	v_cvt_pk_bf16_f32 v66, v68, v69
	v_cvt_pk_bf16_f32 v67, v70, v71
	v_cvt_pk_bf16_f32 v68, v72, v91
	v_cvt_pk_bf16_f32 v69, v92, v93
	v_cvt_pk_bf16_f32 v70, v94, v95
	v_cvt_pk_bf16_f32 v71, v78, v79
	v_cvt_pk_bf16_f32 v72, v80, v81
	v_cvt_pk_bf16_f32 v73, v82, v83
	v_cvt_pk_bf16_f32 v74, v84, v85
	v_cvt_pk_bf16_f32 v75, v86, v87
	v_cvt_pk_bf16_f32 v76, v88, v89
	v_cvt_pk_bf16_f32 v77, v224, v77
	v_cvt_pk_bf16_f32 v78, v225, v226
	v_cvt_pk_bf16_f32 v79, v227, v90
	s_nop 0
	v_permlane32_swap_b32_e32 v64, v66
	v_permlane32_swap_b32_e32 v65, v67
	v_permlane32_swap_b32_e32 v68, v70
	v_permlane32_swap_b32_e32 v69, v71
	v_permlane32_swap_b32_e32 v72, v74
	v_permlane32_swap_b32_e32 v73, v75
	v_permlane32_swap_b32_e32 v76, v78
	v_permlane32_swap_b32_e32 v77, v79
	ds_read_b64_tr_b16 v[80:81], v206 offset:0
	ds_read_b64_tr_b16 v[82:83], v206 offset:0x800
	ds_read_b64_tr_b16 v[84:85], v206 offset:0x1000
	ds_read_b64_tr_b16 v[86:87], v206 offset:0x1800
	ds_read_b64_tr_b16 v[88:89], v206 offset:0x2000
	ds_read_b64_tr_b16 v[90:91], v206 offset:0x2800
	ds_read_b64_tr_b16 v[92:93], v206 offset:0x3000
	ds_read_b64_tr_b16 v[94:95], v206 offset:0x3800
	ds_read_b64_tr_b16 v[224:225], v206 offset:0x200
	ds_read_b64_tr_b16 v[226:227], v206 offset:0xa00
	ds_read_b64_tr_b16 v[228:229], v206 offset:0x1200
	ds_read_b64_tr_b16 v[230:231], v206 offset:0x1a00
	ds_read_b64_tr_b16 v[232:233], v206 offset:0x2200
	ds_read_b64_tr_b16 v[234:235], v206 offset:0x2a00
	ds_read_b64_tr_b16 v[236:237], v206 offset:0x3200
	ds_read_b64_tr_b16 v[238:239], v206 offset:0x3a00
	s_waitcnt lgkmcnt(8)
	s_nop 0
	s_nop 0
	v_mfma_f32_32x32x16_bf16 v[0:15], v[64:67], v[80:83], v[0:15]
	v_mfma_f32_32x32x16_bf16 v[0:15], v[68:71], v[84:87], v[0:15]
	v_mfma_f32_32x32x16_bf16 v[0:15], v[72:75], v[88:91], v[0:15]
	v_mfma_f32_32x32x16_bf16 v[0:15], v[76:79], v[92:95], v[0:15]
	ds_read_b64_tr_b16 v[80:81], v206 offset:0x400
	ds_read_b64_tr_b16 v[82:83], v206 offset:0xc00
	ds_read_b64_tr_b16 v[84:85], v206 offset:0x1400
	ds_read_b64_tr_b16 v[86:87], v206 offset:0x1c00
	ds_read_b64_tr_b16 v[88:89], v206 offset:0x2400
	ds_read_b64_tr_b16 v[90:91], v206 offset:0x2c00
	ds_read_b64_tr_b16 v[92:93], v206 offset:0x3400
	ds_read_b64_tr_b16 v[94:95], v206 offset:0x3c00
	s_waitcnt lgkmcnt(8)
	s_nop 0
	v_mfma_f32_32x32x16_bf16 v[48:63], v[64:67], v[224:227], v[48:63]
	v_mfma_f32_32x32x16_bf16 v[48:63], v[68:71], v[228:231], v[48:63]
	v_mfma_f32_32x32x16_bf16 v[48:63], v[72:75], v[232:235], v[48:63]
	v_mfma_f32_32x32x16_bf16 v[48:63], v[76:79], v[236:239], v[48:63]
	ds_read_b64_tr_b16 v[224:225], v206 offset:0x600
	ds_read_b64_tr_b16 v[226:227], v206 offset:0xe00
	ds_read_b64_tr_b16 v[228:229], v206 offset:0x1600
	ds_read_b64_tr_b16 v[230:231], v206 offset:0x1e00
	ds_read_b64_tr_b16 v[232:233], v206 offset:0x2600
	ds_read_b64_tr_b16 v[234:235], v206 offset:0x2e00
	ds_read_b64_tr_b16 v[236:237], v206 offset:0x3600
	ds_read_b64_tr_b16 v[238:239], v206 offset:0x3e00
	s_waitcnt lgkmcnt(8)
	s_nop 0
	v_mfma_f32_32x32x16_bf16 v[32:47], v[64:67], v[80:83], v[32:47]
	v_mfma_f32_32x32x16_bf16 v[32:47], v[68:71], v[84:87], v[32:47]
	v_mfma_f32_32x32x16_bf16 v[32:47], v[72:75], v[88:91], v[32:47]
	v_mfma_f32_32x32x16_bf16 v[32:47], v[76:79], v[92:95], v[32:47]
	s_waitcnt lgkmcnt(0)
	s_nop 0
	v_mfma_f32_32x32x16_bf16 v[16:31], v[64:67], v[224:227], v[16:31]
	v_mfma_f32_32x32x16_bf16 v[16:31], v[68:71], v[228:231], v[16:31]
	v_mfma_f32_32x32x16_bf16 v[16:31], v[72:75], v[232:235], v[16:31]
	v_mfma_f32_32x32x16_bf16 v[16:31], v[76:79], v[236:239], v[16:31]
	s_waitcnt lgkmcnt(0)
	s_barrier
; #define QSTEP(d, A, B, NA, NB) do { if ((d) + 2 < 12) { NA = KLD((d) + 2, 0); NB = KLD((d) + 2, 1); } SBAR(); \
;     p0 = __builtin_amdgcn_mfma_f32_32x32x16_bf16(A, qr[d], p0, 0, 0, 0); p1 = __builtin_amdgcn_mfma_f32_32x32x16_bf16(B, qr[d], p1, 0, 0, 0); SBAR(); } while (0)
; __device__ __forceinline__ void qkt2(f32x16& p0, f32x16& p1, const char* Ks, const bf16x8* qr, const int* kb4) {
;     ...
;   p0 = f32x16{}; p1 = f32x16{};
;   bf16x8 a0 = KLD(0, 0), b0 = KLD(0, 1), a1 = KLD(1, 0), b1 = KLD(1, 1), a2, b2;
;     ...
;   QSTEP(0, a0, b0, a2, b2); QSTEP(1, a1, b1, a0, b0); QSTEP(2, a2, b2, a1, b1);
;   QSTEP(3, a0, b0, a2, b2); QSTEP(4, a1, b1, a0, b0); QSTEP(5, a2, b2, a1, b1);
;   QSTEP(6, a0, b0, a2, b2); QSTEP(7, a1, b1, a0, b0); QSTEP(8, a2, b2, a1, b1);
;   QSTEP(9, a0, b0, a2, b2); QSTEP(10, a1, b1, a0, b0); QSTEP(11, a2, b2, a1, b1);
;     ...
; }
	v_lshl_add_u64 v[144:145], s[60:61], 0, v[192:193]
	v_lshl_add_u64 v[146:147], s[62:63], 0, v[190:191]
	ds_read_b128 v[64:67], v216 offset:12288
	ds_read_b128 v[194:197], v217 offset:12288
	ds_read_b128 v[224:227], v209 offset:57344
	ds_read_b128 v[228:231], v208 offset:57344
	ds_read_b128 v[68:71], v210 offset:57344
	ds_read_b128 v[232:235], v218 offset:12288
	s_waitcnt vmcnt(0)
	s_cmpk_gt_u32 s44, 0xfd
	s_waitcnt lgkmcnt(1)
	v_mfma_f32_32x32x16_bf16 v[80:95], v[68:71], v[96:99], 0
	v_mfma_f32_32x32x16_bf16 v[64:79], v[64:67], v[96:99], 0
	ds_write_b128 v212, v[164:167]
	ds_write_b128 v212, v[168:171] offset:1024
	ds_read_b128 v[236:239], v207 offset:57344
	ds_read_b128 v[240:243], v219 offset:12288
	v_mfma_f32_32x32x16_bf16 v[80:95], v[224:227], v[100:103], v[80:95]
	v_mfma_f32_32x32x16_bf16 v[64:79], v[194:197], v[100:103], v[64:79]
	ds_write_b128 v211, v[172:175] offset:32768
	ds_write_b128 v211, v[176:179] offset:32896
	ds_read_b128 v[194:197], v210 offset:57472
	ds_read_b128 v[224:227], v216 offset:12416
	s_cbranch_scc1 .Lb2_skip1
	global_load_dwordx4 v[164:167], v[144:145], off offset:256
	global_load_dwordx4 v[168:171], v[144:145], off offset:384
